# m1 plus: GLA scan packs the state to bf16 with v_cvt_pk_bf16_f32 instead of the 6-instruction integer RNE sequence (80 fewer VALU per 2 steps)
# speedup vs baseline: 1.0112x; 1.0035x over previous
.LBB0_777:
	s_mul_i32 s10, s80, 0xab
	s_bfe_u32 s10, s10, 0x70009
	s_mul_i32 s10, s10, 3
	s_sub_i32 s10, s80, s10
	s_and_b32 s10, s10, 0xff
	v_lshl_add_u32 v16, s10, 12, v137
	ds_read_b128 v[124:127], v16
	ds_read_b128 v[120:123], v16 offset:1024
	ds_read_b128 v[116:119], v16 offset:2048
	ds_read_b128 v[112:115], v16 offset:3072
	v_cvt_pk_bf16_f32 v129, v2, v3
	v_cvt_pk_bf16_f32 v128, v0, v1
	v_cvt_pk_bf16_f32 v131, v6, v7
	v_cvt_pk_bf16_f32 v130, v4, v5
	v_cvt_pk_bf16_f32 v133, v10, v11
	v_cvt_pk_bf16_f32 v132, v8, v9
	v_cvt_pk_bf16_f32 v135, v14, v15
	v_cvt_pk_bf16_f32 v134, v12, v13
	s_waitcnt vmcnt(16)
	v_mfma_f32_32x32x16_bf16 v[16:31], v[104:107], v[128:131], 0
	s_and_b64 vcc, exec, s[4:5]
	s_waitcnt vmcnt(7)
	v_mfma_f32_32x32x16_bf16 v[16:31], v[108:111], v[132:135], v[16:31]
	s_cbranch_vccnz .LBB0_793
	s_mov_b64 s[10:11], -1
	s_and_b64 vcc, exec, s[44:45]
	s_cbranch_vccz .LBB0_790
	s_mov_b64 s[54:55], -1
	s_mov_b64 s[10:11], 0
	s_cmp_lt_i32 s65, 2
	s_mov_b64 s[12:13], 0
	s_cbranch_scc1 .LBB0_785
	s_cmp_eq_u32 s65, 2
	s_mov_b64 s[12:13], -1
	s_cbranch_scc0 .LBB0_782
	s_mov_b64 s[12:13], 0
	s_waitcnt vmcnt(4) lgkmcnt(1)
	v_mfma_f32_32x32x16_bf16 v[32:47], v[56:59], v[116:119], v[16:31]

.LBB0_813:
	s_waitcnt lgkmcnt(0)
	s_barrier
	ds_read2st64_b32 v[16:17], v239 offset1:1
	ds_read2st64_b32 v[18:19], v239 offset0:32 offset1:33
	ds_read2st64_b32 v[20:21], v239 offset0:64 offset1:65
	ds_read2st64_b32 v[22:23], v239 offset0:96 offset1:97
	ds_read2st64_b32 v[24:25], v239 offset0:128 offset1:129
	ds_read2st64_b32 v[26:27], v239 offset0:160 offset1:161
	ds_read2st64_b32 v[28:29], v239 offset0:192 offset1:193
	ds_read2st64_b32 v[30:31], v239 offset0:224 offset1:225
	s_waitcnt lgkmcnt(7)
	v_add_f32_e32 v16, 0, v16
	s_waitcnt lgkmcnt(6)
	v_add_f32_e32 v16, v16, v18
	s_waitcnt lgkmcnt(5)
	v_add_f32_e32 v16, v16, v20
	s_waitcnt lgkmcnt(4)
	v_add_f32_e32 v16, v16, v22
	s_waitcnt lgkmcnt(3)
	v_add_f32_e32 v16, v16, v24
	s_waitcnt lgkmcnt(2)
	v_add_f32_e32 v16, v16, v26
	s_waitcnt lgkmcnt(1)
	v_add_f32_e32 v16, v16, v28
	s_waitcnt lgkmcnt(0)
	v_add_f32_e32 v16, v16, v30
	v_bfe_u32 v18, v16, 16, 1
	v_add3_u32 v16, v16, v18, s31
	v_lshl_add_u64 v[32:33], s[96:97], 0, v[222:223]
	global_store_short_d16_hi v[32:33], v16, off
	v_add_f32_e32 v16, 0, v17
	v_add_f32_e32 v16, v16, v19
	v_add_f32_e32 v16, v16, v21
	v_add_f32_e32 v16, v16, v23
	v_add_f32_e32 v16, v16, v25
	v_add_f32_e32 v16, v16, v27
	v_add_f32_e32 v16, v16, v29
	v_add_f32_e32 v16, v16, v31
	v_bfe_u32 v17, v16, 16, 1
	v_add3_u32 v20, v16, v17, s31
	v_lshl_add_u64 v[16:17], s[96:97], 0, v[220:221]
	v_add_co_u32_e32 v18, vcc, s76, v16
	ds_read2st64_b32 v[22:23], v239 offset0:34 offset1:35
	ds_read2st64_b32 v[24:25], v239 offset0:66 offset1:67
	ds_read2st64_b32 v[26:27], v239 offset0:98 offset1:99
	v_addc_co_u32_e32 v19, vcc, 0, v17, vcc
	global_store_short_d16_hi v[18:19], v20, off offset:-4096
	ds_read2st64_b32 v[20:21], v239 offset0:2 offset1:3
	ds_read2st64_b32 v[28:29], v239 offset0:130 offset1:131
	ds_read2st64_b32 v[30:31], v239 offset0:162 offset1:163
	ds_read2st64_b32 v[32:33], v239 offset0:194 offset1:195
	ds_read2st64_b32 v[34:35], v239 offset0:226 offset1:227
	s_waitcnt lgkmcnt(4)
	v_add_f32_e32 v20, 0, v20
	v_add_f32_e32 v20, v20, v22
	v_add_f32_e32 v20, v20, v24
	v_add_f32_e32 v20, v20, v26
	s_waitcnt lgkmcnt(3)
	v_add_f32_e32 v20, v20, v28
	s_waitcnt lgkmcnt(2)
	v_add_f32_e32 v20, v20, v30
	s_waitcnt lgkmcnt(1)
	v_add_f32_e32 v20, v20, v32
	s_waitcnt lgkmcnt(0)
	v_add_f32_e32 v20, v20, v34
	v_bfe_u32 v22, v20, 16, 1
	v_add3_u32 v20, v20, v22, s31
	global_store_short_d16_hi v[18:19], v20, off
	v_add_f32_e32 v18, 0, v21
	v_add_f32_e32 v18, v18, v23
	v_add_f32_e32 v18, v18, v25
	v_add_f32_e32 v18, v18, v27
	v_add_f32_e32 v18, v18, v29
	v_add_f32_e32 v18, v18, v31
	v_add_f32_e32 v18, v18, v33
	v_add_f32_e32 v18, v18, v35
	s_mov_b32 s13, 0x2d403000
	v_bfe_u32 v19, v18, 16, 1
	v_add_co_u32_e32 v16, vcc, s13, v16
	v_add3_u32 v18, v18, v19, s31
	s_nop 0
	v_addc_co_u32_e32 v17, vcc, 0, v17, vcc
	global_store_short_d16_hi v[16:17], v18, off
	v_add_u32_e32 v16, s12, v137
	ds_read_b128 v[124:127], v16
	ds_read_b128 v[120:123], v16 offset:1024
	ds_read_b128 v[116:119], v16 offset:2048
	ds_read_b128 v[112:115], v16 offset:3072
	v_cvt_pk_bf16_f32 v129, v2, v3
	v_cvt_pk_bf16_f32 v128, v0, v1
	v_cvt_pk_bf16_f32 v131, v6, v7
	v_cvt_pk_bf16_f32 v130, v4, v5
	v_cvt_pk_bf16_f32 v133, v10, v11
	v_cvt_pk_bf16_f32 v132, v8, v9
	v_cvt_pk_bf16_f32 v135, v14, v15
	v_cvt_pk_bf16_f32 v134, v12, v13
	s_waitcnt vmcnt(16)
	v_mfma_f32_32x32x16_bf16 v[16:31], v[104:107], v[128:131], 0
	s_and_b64 vcc, exec, s[4:5]
	s_waitcnt vmcnt(15)
	v_mfma_f32_32x32x16_bf16 v[16:31], v[108:111], v[132:135], v[16:31]
	s_cbranch_vccnz .LBB0_829
	s_mov_b64 s[12:13], -1
	s_and_b64 vcc, exec, s[44:45]
	s_cbranch_vccz .LBB0_826
	s_mov_b64 s[60:61], -1
	s_mov_b64 s[12:13], 0
	s_cmp_lt_i32 s65, 2
	s_mov_b64 s[58:59], 0
	s_cbranch_scc1 .LBB0_821
	s_cmp_eq_u32 s65, 2
	s_mov_b64 s[58:59], -1
	s_cbranch_scc0 .LBB0_818
	s_mov_b64 s[58:59], 0
	s_waitcnt vmcnt(12) lgkmcnt(1)
	v_mfma_f32_32x32x16_bf16 v[32:47], v[56:59], v[116:119], v[16:31]
